# compute list order: gate-GEMM units moved behind the five longest attention classes (tickets 320..383)
# speedup vs baseline: 1.0153x; 1.0019x over previous
; #define KPTR(T, ap64, i) ((T*)(__attribute__((address_space(1))) T*)(ap64)[i])
; __global__ void __launch_bounds__(512, 2) mk_fwd(MKArgs args) {
;     ...
;                   __syncthreads();
;                   const unsigned kind = LQ[0], idx = LQ[1];
;                   __syncthreads();
;                   if (kind == 2u) break;
;                   if (kind == 0u) { PHASE_IDS sample_attn_task(l, (int)idx, tid, ldsl + RING_OFF, ws, KPTR(const float, ap, 2), KPTR(const float, ap, 3), (const int*)KPTR(const float, ap, 4), KPTR(const float, ap, 24)); }
;                   else if (idx < (unsigned)(M / 256)) {
;                       pg8::Gemm g{(const bf16_t*)(ws + WS_Y5), (const bf16_t*)(wl + WL_GLU), M, 256, 256}; const pg8::OneUnitPub S{(int)idx, 0, (unsigned*)(ws + WS_CTL) + CW_MX + (l * 64 + (int)idx) * 64};
;                       pg8::EpiGlu E{(const bf16_t*)(ws + WS_Y5), KPTR(const float, ap, 19) + l * 256, (bf16_t*)(ws + WS_MIX)};
;                       pg8::gemm_phase<pg8::EpiGlu, pg8::OneUnitPub, true, true>(ldsl + RING_OFF, g, S, E, wave_s); }
;                   else { const int ia = (int)idx - M / 256, qb = 7 - (ia >> 6), bh = ia & 63;
.LBB0_1262:
	v_mov_b32_e32 v0, s51
	s_waitcnt lgkmcnt(0)
	s_barrier
	ds_read_b32 v0, v0
	s_mov_b64 s[8:9], -1
	s_mov_b64 s[4:5], 0
	s_mov_b64 s[6:7], 0
	s_waitcnt lgkmcnt(0)
	v_readfirstlane_b32 s10, v0
	v_mov_b32_e32 v0, s52
	ds_read_b32 v0, v0
	s_cmp_lt_i32 s10, 2
	s_waitcnt lgkmcnt(0)
	s_barrier
	v_readfirstlane_b32 s79, v0
	s_cmp_eq_u32 s10, 1
	s_cbranch_scc0 .Lq3_noremap
	s_cmpk_gt_u32 s79, 0x17f
	s_cbranch_scc1 .Lq3_noremap
	s_add_i32 s79, s79, 64
	s_cmpk_lt_u32 s79, 0x180
	s_cbranch_scc1 .Lq3_noremap
	s_sub_i32 s79, s79, 0x180
